# grid barrier: arrival atomic and buffer_inv issued back to back; XCD leader overlaps its buffer_wbl2 with its own invalidate and checks a per-XCD invalidate-done counter before the top-level add
# baseline (speedup 1.0000x reference)
.LBB0_1457:
	v_readlane_b32 s4, v254, 54
	v_readlane_b32 s5, v254, 55
	v_readlane_b32 s6, v254, 56
	v_readlane_b32 s7, v254, 57
	v_readlane_b32 s8, v254, 58
	v_readlane_b32 s9, v254, 59
	v_mov_b32_e32 v3, 1
	s_waitcnt lgkmcnt(0)
	s_nop 1
	global_atomic_add v3, v177, v3, s[4:5] sc0
	buffer_inv sc1
	v_cvt_f32_u32_e32 v4, v2
	v_sub_u32_e32 v6, 0, v2
	v_rcp_iflag_f32_e32 v4, v4
	s_nop 0
	v_mul_f32_e32 v4, 0x4f7ffffe, v4
	v_cvt_u32_f32_e32 v4, v4
	v_mul_lo_u32 v1, v6, v4
	v_mul_hi_u32 v1, v4, v1
	v_add_u32_e32 v1, v4, v1
	s_waitcnt vmcnt(1)
	v_mov_b32_e32 v5, v3
	v_mul_hi_u32 v1, v5, v1
	v_mul_lo_u32 v3, v1, v2
	v_sub_u32_e32 v3, v5, v3
	v_add_u32_e32 v4, 1, v1
	v_cmp_ge_u32_e32 vcc, v3, v2
	s_nop 1
	v_cndmask_b32_e32 v1, v1, v4, vcc
	v_sub_u32_e32 v4, v3, v2
	v_cndmask_b32_e32 v3, v3, v4, vcc
	v_add_u32_e32 v4, 1, v1
	v_cmp_ge_u32_e32 vcc, v3, v2
	v_add_u32_e32 v3, 1, v5
	s_nop 0
	v_cndmask_b32_e32 v1, v1, v4, vcc
	v_add_u32_e32 v1, 1, v1
	v_mul_lo_u32 v4, v2, v1
	v_mul_lo_u32 v1, v1, v0
	v_cmp_ne_u32_e32 vcc, v3, v4
	s_mov_b32 s16, 0
	v_mov_b32_e32 v2, 1
	s_cbranch_vccnz .Lxb_nl
	buffer_wbl2 sc1
	s_waitcnt vmcnt(0)
	global_atomic_add v3, v177, v2, s[6:7] sc0
	s_waitcnt vmcnt(0)
	v_add_u32_e32 v3, 1, v3
	v_cmp_eq_u32_e32 vcc, v3, v4
	s_cbranch_vccnz .Lxb_top
.Lxb_w2:
	global_load_dword v3, v177, s[6:7] sc1
	s_waitcnt vmcnt(0)
	v_sub_u32_e32 v3, v3, v4
	v_cmp_le_i32_e32 vcc, 0, v3
	s_cbranch_vccnz .Lxb_top
	s_sleep 1
	s_add_i32 s16, s16, 1
	s_cmp_lt_u32 s16, 0x100000
	s_cbranch_scc1 .Lxb_w2
	global_atomic_add v177, v2, s[82:83]
.Lxb_top:
	s_mov_b32 s16, 0
	global_atomic_add v177, v2, s[8:9]
	s_branch .Lxb_spin
.Lxb_nl:
	s_waitcnt vmcnt(0)
	global_atomic_add v177, v2, s[6:7]
.Lxb_spin:
	global_load_dword v0, v177, s[8:9] sc1
	s_waitcnt vmcnt(0)
	v_sub_u32_e32 v0, v0, v1
	v_cmp_le_i32_e32 vcc, 0, v0
	s_cbranch_vccnz .Lxb_done
	s_sleep 1
	s_add_i32 s16, s16, 1
	s_and_b32 s12, s16, 0xff
	s_cmp_lg_u32 s12, 0
	s_cbranch_scc1 .Lxb_spin
	global_load_dword v0, v177, s[82:83] sc1
	s_waitcnt vmcnt(0)
	v_cmp_ne_u32_e32 vcc, 0, v0
	s_cbranch_vccnz .Lxb_done
	s_cmp_lt_u32 s16, 0x400001
	s_cbranch_scc1 .Lxb_spin
	v_mov_b32_e32 v0, 1
	global_atomic_add v177, v0, s[82:83]
